# rg_conv re-mapped: one channel octet per thread (weights and bias loaded once instead of per item), rows strided by 819, next row's tap loads issued before the current row's math
# speedup vs baseline: 1.0106x; 1.0020x over previous
; __device__ __forceinline__ unsigned pk2(float lo, float hi) { f32x2_pk v = {lo, hi}; bf16x2_pk b = __builtin_convertvector(v, bf16x2_pk); return __builtin_bit_cast(unsigned, b); }
; __device__ __forceinline__ void rg_conv_phase(const bf16_t* XR, bf16_t* XCV, const float* cw, const float* cb, int gtid, int ngt) {
;     for (int it = gtid; it < MT * 160; it += ngt) { const int m = it / 160, c8 = (it % 160) * 8;
;         int t, L; if (m < ML) { t = m & 2047; L = SEQ; } else { t = (m - ML) & 255; L = CTX; }
;         float o[8];
; #pragma unroll
;         for (int e = 0; e < 8; ++e) o[e] = cb[c8 + e];
; #pragma unroll
;         for (int k = 0; k < 4; ++k) { const int tt = t + k - 2; if (tt < 0 || tt >= L) continue;
;             const u32x4 w = *(const u32x4*)(XR + (size_t)(m + k - 2) * DRNN + c8); const float* wk = cw + k * DRNN + c8;
;             o[0] += wk[0] * bflo(w.x); o[1] += wk[1] * bfhi(w.x); o[2] += wk[2] * bflo(w.y); o[3] += wk[3] * bfhi(w.y); o[4] += wk[4] * bflo(w.z); o[5] += wk[5] * bfhi(w.z); o[6] += wk[6] * bflo(w.w); o[7] += wk[7] * bfhi(w.w); }
;         u32x4 r; r.x = pk2(o[0], o[1]); r.y = pk2(o[2], o[3]); r.z = pk2(o[4], o[5]); r.w = pk2(o[6], o[7]);
;         *(u32x4*)(XCV + (size_t)m * DRNN + c8) = r; }
; }
.LBB0_814:
	s_add_i32 s1, s75, 1
	s_cmp_le_i32 s70, s1
	s_cselect_b64 s[2:3], -1, 0
	s_cmp_lt_i32 s1, s71
	s_cselect_b64 s[6:7], -1, 0
	s_and_b64 s[2:3], s[2:3], s[6:7]
	s_andn2_b64 vcc, exec, s[2:3]
	s_cbranch_vccnz .LBB0_827
	v_mov_b32_e32 v0, v198
	s_mov_b32 s2, s91
	s_mov_b64 s[6:7], s[84:85]
	v_lshl_add_u32 v9, s2, 9, v0
	s_mov_b32 s2, 0x5a0000
	v_cmp_gt_i32_e32 vcc, s2, v9
	s_and_saveexec_b64 s[16:17], vcc
	s_cbranch_execz .LBB0_826
	s_load_dwordx4 s[8:11], s[6:7], 0x120
	s_load_dwordx4 s[12:15], s[6:7], 0x48
	v_lshlrev_b32_e32 v8, 3, v9
	s_mov_b64 s[18:19], 0
	s_waitcnt lgkmcnt(0)
	s_add_u32 s10, s10, 0x8a00000
	s_addc_u32 s11, s11, 0
	s_lshl_b32 s2, s33, 3
	s_mov_b32 s3, 0x1ffe0
	v_cmp_gt_u32_e32 vcc, s3, v9
	s_and_saveexec_b64 s[18:19], vcc
	s_cbranch_execz .Lconv_done
	v_mul_hi_i32 v104, v9, s43
	v_lshrrev_b32_e32 v105, 31, v104
	v_ashrrev_i32_e32 v104, 6, v104
	v_add_u32_e32 v120, v104, v105
	s_movk_i32 s3, 0xfb00
	v_mad_u64_u32 v[122:123], s[6:7], v120, s3, v[8:9]
	v_ashrrev_i32_e32 v123, 31, v122
	v_lshlrev_b64 v[104:105], 2, v[122:123]
	v_lshl_add_u64 v[106:107], s[14:15], 0, v[104:105]
	global_load_dwordx4 v[96:99], v[106:107], off
	global_load_dwordx4 v[100:103], v[106:107], off offset:16
	v_lshl_add_u64 v[104:105], s[12:13], 0, v[104:105]
	global_load_dwordx4 v[64:67], v[104:105], off
	global_load_dwordx4 v[68:71], v[104:105], off offset:16
	s_mov_b64 s[100:101], 0x1000
	v_lshl_add_u64 v[106:107], v[104:105], 0, s[100:101]
	global_load_dwordx4 v[72:75], v[106:107], off offset:1024
	global_load_dwordx4 v[76:79], v[106:107], off offset:1040
	s_mov_b64 s[100:101], 0x2000
	v_lshl_add_u64 v[106:107], v[104:105], 0, s[100:101]
	global_load_dwordx4 v[80:83], v[106:107], off offset:2048
	global_load_dwordx4 v[84:87], v[106:107], off offset:2064
	s_mov_b64 s[100:101], 0x3000
	v_lshl_add_u64 v[106:107], v[104:105], 0, s[100:101]
	global_load_dwordx4 v[88:91], v[106:107], off offset:3072
	global_load_dwordx4 v[92:95], v[106:107], off offset:3088
	v_lshl_add_u64 v[124:125], v[122:123], 1, s[8:9]
	v_lshl_add_u64 v[126:127], v[122:123], 1, s[10:11]
	v_mov_b32_e32 v121, v120
	s_movk_i32 s2, 22
	v_mov_b32_e32 v24, v121
	s_mov_b32 s3, 0x8000
	v_cmp_gt_i32_e32 vcc, s3, v24
	v_mov_b32_e32 v104, 0x7ff
	v_mov_b32_e32 v105, 0x802
	v_cndmask_b32_e32 v104, v216, v104, vcc
	v_and_b32_e32 v25, v104, v24
	v_bfrev_b32_e32 v104, 4.0
	v_cndmask_b32_e32 v26, v104, v105, vcc
	s_movk_i32 s3, 0xa00
	v_cmp_lt_u32_e32 vcc, 1, v25
	v_cmp_lt_u32_e64 s[6:7], v25, v26
	v_add_u32_e32 v106, -2, v24
	s_nop 1
	s_and_b64 vcc, vcc, s[6:7]
	s_nop 1
	v_cndmask_b32_e32 v106, v24, v106, vcc
	v_mad_i64_i32 v[108:109], s[20:21], v106, s3, v[124:125]
	global_load_dwordx4 v[8:11], v[108:109], off
	v_add_u32_e32 v107, 1, v25
	v_cmp_ne_u32_e32 vcc, 0, v25
	v_cmp_lt_u32_e64 s[6:7], v107, v26
	v_add_u32_e32 v106, -1, v24
	s_nop 1
	s_and_b64 vcc, vcc, s[6:7]
	s_nop 1
	v_cndmask_b32_e32 v106, v24, v106, vcc
	v_mad_i64_i32 v[108:109], s[20:21], v106, s3, v[124:125]
	global_load_dwordx4 v[12:15], v[108:109], off
	v_mad_i64_i32 v[108:109], s[20:21], v24, s3, v[124:125]
	global_load_dwordx4 v[16:19], v[108:109], off
	v_add_u32_e32 v107, 3, v25
	v_add_u32_e32 v106, 1, v24
	v_cmp_lt_u32_e32 vcc, v107, v26
	s_nop 1
	v_cndmask_b32_e32 v106, v24, v106, vcc
	v_mad_i64_i32 v[108:109], s[20:21], v106, s3, v[124:125]
	global_load_dwordx4 v[20:23], v[108:109], off
	v_add_u32_e32 v121, 0x333, v121
.Lconv_loop:
	v_mov_b32_e32 v56, v121
	s_mov_b32 s3, 0x8000
	v_cmp_gt_i32_e32 vcc, s3, v56
	v_mov_b32_e32 v104, 0x7ff
	v_mov_b32_e32 v105, 0x802
	v_cndmask_b32_e32 v104, v216, v104, vcc
	v_and_b32_e32 v57, v104, v56
	v_bfrev_b32_e32 v104, 4.0
	v_cndmask_b32_e32 v58, v104, v105, vcc
	s_movk_i32 s3, 0xa00
	v_cmp_lt_u32_e32 vcc, 1, v57
	v_cmp_lt_u32_e64 s[6:7], v57, v58
	v_add_u32_e32 v106, -2, v56
	s_nop 1
	s_and_b64 vcc, vcc, s[6:7]
	s_nop 1
	v_cndmask_b32_e32 v106, v56, v106, vcc
	v_mad_i64_i32 v[108:109], s[20:21], v106, s3, v[124:125]
	global_load_dwordx4 v[40:43], v[108:109], off
	v_add_u32_e32 v107, 1, v57
	v_cmp_ne_u32_e32 vcc, 0, v57
	v_cmp_lt_u32_e64 s[6:7], v107, v58
	v_add_u32_e32 v106, -1, v56
	s_nop 1
	s_and_b64 vcc, vcc, s[6:7]
	s_nop 1
	v_cndmask_b32_e32 v106, v56, v106, vcc
	v_mad_i64_i32 v[108:109], s[20:21], v106, s3, v[124:125]
	global_load_dwordx4 v[44:47], v[108:109], off
	v_mad_i64_i32 v[108:109], s[20:21], v56, s3, v[124:125]
	global_load_dwordx4 v[48:51], v[108:109], off
	v_add_u32_e32 v107, 3, v57
	v_add_u32_e32 v106, 1, v56
	v_cmp_lt_u32_e32 vcc, v107, v58
	s_nop 1
	v_cndmask_b32_e32 v106, v56, v106, vcc
	v_mad_i64_i32 v[108:109], s[20:21], v106, s3, v[124:125]
	global_load_dwordx4 v[52:55], v[108:109], off
	v_add_u32_e32 v121, 0x333, v121
	s_waitcnt vmcnt(4)
; __device__ __forceinline__ unsigned pk2(float lo, float hi) { f32x2_pk v = {lo, hi}; bf16x2_pk b = __builtin_convertvector(v, bf16x2_pk); return __builtin_bit_cast(unsigned, b); }
; __device__ __forceinline__ void rg_conv_phase(const bf16_t* XR, bf16_t* XCV, const float* cw, const float* cb, int gtid, int ngt) {
;     ...
;         int t, L; if (m < ML) { t = m & 2047; L = SEQ; } else { t = (m - ML) & 255; L = CTX; }
;         float o[8];
; #pragma unroll
;         for (int e = 0; e < 8; ++e) o[e] = cb[c8 + e];
; #pragma unroll
;         for (int k = 0; k < 4; ++k) { const int tt = t + k - 2; if (tt < 0 || tt >= L) continue;
;             const u32x4 w = *(const u32x4*)(XR + (size_t)(m + k - 2) * DRNN + c8); const float* wk = cw + k * DRNN + c8;
;             o[0] += wk[0] * bflo(w.x); o[1] += wk[1] * bfhi(w.x); o[2] += wk[2] * bflo(w.y); o[3] += wk[3] * bfhi(w.y); o[4] += wk[4] * bflo(w.z); o[5] += wk[5] * bfhi(w.z); o[6] += wk[6] * bflo(w.w); o[7] += wk[7] * bfhi(w.w); }
;         u32x4 r; r.x = pk2(o[0], o[1]); r.y = pk2(o[2], o[3]); r.z = pk2(o[4], o[5]); r.w = pk2(o[6], o[7]);
;         *(u32x4*)(XCV + (size_t)m * DRNN + c8) = r; }
	v_cmp_lt_u32_e32 vcc, 1, v25
	v_cmp_lt_u32_e64 s[6:7], v25, v26
	v_add_u32_e32 v107, 1, v25
	s_nop 1
	s_and_b64 vcc, vcc, s[6:7]
	s_nop 1
	v_cndmask_b32_e32 v8, 0, v8, vcc
	v_cndmask_b32_e32 v9, 0, v9, vcc
	v_cndmask_b32_e32 v10, 0, v10, vcc
	v_cndmask_b32_e32 v11, 0, v11, vcc
	v_cmp_ne_u32_e32 vcc, 0, v25
	v_cmp_lt_u32_e64 s[6:7], v107, v26
	v_add_u32_e32 v106, 2, v25
	s_nop 1
	s_and_b64 vcc, vcc, s[6:7]
	s_nop 1
	v_cndmask_b32_e32 v12, 0, v12, vcc
	v_cndmask_b32_e32 v13, 0, v13, vcc
	v_cndmask_b32_e32 v14, 0, v14, vcc
	v_cndmask_b32_e32 v15, 0, v15, vcc
	v_cmp_lt_u32_e32 vcc, v106, v26
	v_add_u32_e32 v107, 3, v25
	s_nop 1
	v_cndmask_b32_e32 v16, 0, v16, vcc
	v_cndmask_b32_e32 v17, 0, v17, vcc
	v_cndmask_b32_e32 v18, 0, v18, vcc
	v_cndmask_b32_e32 v19, 0, v19, vcc
	v_cmp_lt_u32_e32 vcc, v107, v26
	s_nop 1
	s_nop 0
	v_cndmask_b32_e32 v20, 0, v20, vcc
	v_cndmask_b32_e32 v21, 0, v21, vcc
	v_cndmask_b32_e32 v22, 0, v22, vcc
	v_cndmask_b32_e32 v23, 0, v23, vcc
	v_lshlrev_b32_e32 v106, 16, v8
	v_and_b32_e32 v107, 0xffff0000, v8
	v_pk_fma_f32 v[4:5], v[64:65], v[106:107], v[96:97]
	v_lshlrev_b32_e32 v106, 16, v9
	v_and_b32_e32 v107, 0xffff0000, v9
	v_pk_fma_f32 v[6:7], v[66:67], v[106:107], v[98:99]
	v_lshlrev_b32_e32 v106, 16, v10
	v_and_b32_e32 v107, 0xffff0000, v10
	v_pk_fma_f32 v[0:1], v[68:69], v[106:107], v[100:101]
	v_lshlrev_b32_e32 v106, 16, v11
	v_and_b32_e32 v107, 0xffff0000, v11
	v_pk_fma_f32 v[2:3], v[70:71], v[106:107], v[102:103]
	v_lshlrev_b32_e32 v106, 16, v12
	v_and_b32_e32 v107, 0xffff0000, v12
	v_pk_fma_f32 v[4:5], v[72:73], v[106:107], v[4:5]
	v_lshlrev_b32_e32 v106, 16, v13
	v_and_b32_e32 v107, 0xffff0000, v13
	v_pk_fma_f32 v[6:7], v[74:75], v[106:107], v[6:7]
	v_lshlrev_b32_e32 v106, 16, v14
	v_and_b32_e32 v107, 0xffff0000, v14
	v_pk_fma_f32 v[0:1], v[76:77], v[106:107], v[0:1]
	v_lshlrev_b32_e32 v106, 16, v15
	v_and_b32_e32 v107, 0xffff0000, v15
	v_pk_fma_f32 v[2:3], v[78:79], v[106:107], v[2:3]
	v_lshlrev_b32_e32 v106, 16, v16
	v_and_b32_e32 v107, 0xffff0000, v16
	v_pk_fma_f32 v[4:5], v[80:81], v[106:107], v[4:5]
	v_lshlrev_b32_e32 v106, 16, v17
	v_and_b32_e32 v107, 0xffff0000, v17
	v_pk_fma_f32 v[6:7], v[82:83], v[106:107], v[6:7]
	v_lshlrev_b32_e32 v106, 16, v18
	v_and_b32_e32 v107, 0xffff0000, v18
	v_pk_fma_f32 v[0:1], v[84:85], v[106:107], v[0:1]
	v_lshlrev_b32_e32 v106, 16, v19
	v_and_b32_e32 v107, 0xffff0000, v19
	v_pk_fma_f32 v[2:3], v[86:87], v[106:107], v[2:3]
	v_lshlrev_b32_e32 v106, 16, v20
	v_and_b32_e32 v107, 0xffff0000, v20
	v_pk_fma_f32 v[4:5], v[88:89], v[106:107], v[4:5]
	v_lshlrev_b32_e32 v106, 16, v21
	v_and_b32_e32 v107, 0xffff0000, v21
	v_pk_fma_f32 v[6:7], v[90:91], v[106:107], v[6:7]
	v_lshlrev_b32_e32 v106, 16, v22
	v_and_b32_e32 v107, 0xffff0000, v22
	v_pk_fma_f32 v[0:1], v[92:93], v[106:107], v[0:1]
	v_lshlrev_b32_e32 v106, 16, v23
	v_and_b32_e32 v107, 0xffff0000, v23
	v_pk_fma_f32 v[2:3], v[94:95], v[106:107], v[2:3]
	v_cvt_pk_bf16_f32 v110, v4, v5
	v_cvt_pk_bf16_f32 v111, v6, v7
	v_cvt_pk_bf16_f32 v112, v0, v1
	v_cvt_pk_bf16_f32 v113, v2, v3
	s_movk_i32 s3, 0xa00
	v_mad_i64_i32 v[108:109], s[6:7], v24, s3, v[126:127]
	global_store_dwordx4 v[108:109], v[110:113], off
	s_nop 1
	v_mov_b32_e32 v24, v121
	s_mov_b32 s3, 0x8000
	v_cmp_gt_i32_e32 vcc, s3, v24
	v_mov_b32_e32 v104, 0x7ff
	v_mov_b32_e32 v105, 0x802
	v_cndmask_b32_e32 v104, v216, v104, vcc
	v_and_b32_e32 v25, v104, v24
	v_bfrev_b32_e32 v104, 4.0
	v_cndmask_b32_e32 v26, v104, v105, vcc
	s_movk_i32 s3, 0xa00
	v_cmp_lt_u32_e32 vcc, 1, v25
	v_cmp_lt_u32_e64 s[6:7], v25, v26
	v_add_u32_e32 v106, -2, v24
	s_nop 1
	s_and_b64 vcc, vcc, s[6:7]
	s_nop 1
	v_cndmask_b32_e32 v106, v24, v106, vcc
	v_mad_i64_i32 v[108:109], s[20:21], v106, s3, v[124:125]
	global_load_dwordx4 v[8:11], v[108:109], off
	v_add_u32_e32 v107, 1, v25
	v_cmp_ne_u32_e32 vcc, 0, v25
	v_cmp_lt_u32_e64 s[6:7], v107, v26
	v_add_u32_e32 v106, -1, v24
	s_nop 1
	s_and_b64 vcc, vcc, s[6:7]
	s_nop 1
	v_cndmask_b32_e32 v106, v24, v106, vcc
	v_mad_i64_i32 v[108:109], s[20:21], v106, s3, v[124:125]
	global_load_dwordx4 v[12:15], v[108:109], off
	v_mad_i64_i32 v[108:109], s[20:21], v24, s3, v[124:125]
	global_load_dwordx4 v[16:19], v[108:109], off
	v_add_u32_e32 v107, 3, v25
	v_add_u32_e32 v106, 1, v24
	v_cmp_lt_u32_e32 vcc, v107, v26
	s_nop 1
	v_cndmask_b32_e32 v106, v24, v106, vcc
	v_mad_i64_i32 v[108:109], s[20:21], v106, s3, v[124:125]
	global_load_dwordx4 v[20:23], v[108:109], off
	v_add_u32_e32 v121, 0x333, v121
	s_waitcnt vmcnt(5)
; __device__ __forceinline__ unsigned pk2(float lo, float hi) { f32x2_pk v = {lo, hi}; bf16x2_pk b = __builtin_convertvector(v, bf16x2_pk); return __builtin_bit_cast(unsigned, b); }
; __device__ __forceinline__ void rg_conv_phase(const bf16_t* XR, bf16_t* XCV, const float* cw, const float* cb, int gtid, int ngt) {
;     ...
;         int t, L; if (m < ML) { t = m & 2047; L = SEQ; } else { t = (m - ML) & 255; L = CTX; }
;         float o[8];
; #pragma unroll
;         for (int e = 0; e < 8; ++e) o[e] = cb[c8 + e];
; #pragma unroll
;         for (int k = 0; k < 4; ++k) { const int tt = t + k - 2; if (tt < 0 || tt >= L) continue;
;             const u32x4 w = *(const u32x4*)(XR + (size_t)(m + k - 2) * DRNN + c8); const float* wk = cw + k * DRNN + c8;
;             o[0] += wk[0] * bflo(w.x); o[1] += wk[1] * bfhi(w.x); o[2] += wk[2] * bflo(w.y); o[3] += wk[3] * bfhi(w.y); o[4] += wk[4] * bflo(w.z); o[5] += wk[5] * bfhi(w.z); o[6] += wk[6] * bflo(w.w); o[7] += wk[7] * bfhi(w.w); }
;         u32x4 r; r.x = pk2(o[0], o[1]); r.y = pk2(o[2], o[3]); r.z = pk2(o[4], o[5]); r.w = pk2(o[6], o[7]);
;         *(u32x4*)(XCV + (size_t)m * DRNN + c8) = r; }
	v_cmp_lt_u32_e32 vcc, 1, v57
	v_cmp_lt_u32_e64 s[6:7], v57, v58
	v_add_u32_e32 v107, 1, v57
	s_nop 1
	s_and_b64 vcc, vcc, s[6:7]
	s_nop 1
	v_cndmask_b32_e32 v40, 0, v40, vcc
	v_cndmask_b32_e32 v41, 0, v41, vcc
	v_cndmask_b32_e32 v42, 0, v42, vcc
	v_cndmask_b32_e32 v43, 0, v43, vcc
	v_cmp_ne_u32_e32 vcc, 0, v57
	v_cmp_lt_u32_e64 s[6:7], v107, v58
	v_add_u32_e32 v106, 2, v57
	s_nop 1
	s_and_b64 vcc, vcc, s[6:7]
	s_nop 1
	v_cndmask_b32_e32 v44, 0, v44, vcc
	v_cndmask_b32_e32 v45, 0, v45, vcc
	v_cndmask_b32_e32 v46, 0, v46, vcc
	v_cndmask_b32_e32 v47, 0, v47, vcc
	v_cmp_lt_u32_e32 vcc, v106, v58
	v_add_u32_e32 v107, 3, v57
	s_nop 1
	v_cndmask_b32_e32 v48, 0, v48, vcc
	v_cndmask_b32_e32 v49, 0, v49, vcc
	v_cndmask_b32_e32 v50, 0, v50, vcc
	v_cndmask_b32_e32 v51, 0, v51, vcc
	v_cmp_lt_u32_e32 vcc, v107, v58
	s_nop 1
	s_nop 0
	v_cndmask_b32_e32 v52, 0, v52, vcc
	v_cndmask_b32_e32 v53, 0, v53, vcc
	v_cndmask_b32_e32 v54, 0, v54, vcc
	v_cndmask_b32_e32 v55, 0, v55, vcc
	v_lshlrev_b32_e32 v106, 16, v40
	v_and_b32_e32 v107, 0xffff0000, v40
	v_pk_fma_f32 v[36:37], v[64:65], v[106:107], v[96:97]
	v_lshlrev_b32_e32 v106, 16, v41
	v_and_b32_e32 v107, 0xffff0000, v41
	v_pk_fma_f32 v[38:39], v[66:67], v[106:107], v[98:99]
	v_lshlrev_b32_e32 v106, 16, v42
	v_and_b32_e32 v107, 0xffff0000, v42
	v_pk_fma_f32 v[32:33], v[68:69], v[106:107], v[100:101]
	v_lshlrev_b32_e32 v106, 16, v43
	v_and_b32_e32 v107, 0xffff0000, v43
	v_pk_fma_f32 v[34:35], v[70:71], v[106:107], v[102:103]
	v_lshlrev_b32_e32 v106, 16, v44
	v_and_b32_e32 v107, 0xffff0000, v44
	v_pk_fma_f32 v[36:37], v[72:73], v[106:107], v[36:37]
	v_lshlrev_b32_e32 v106, 16, v45
	v_and_b32_e32 v107, 0xffff0000, v45
	v_pk_fma_f32 v[38:39], v[74:75], v[106:107], v[38:39]
	v_lshlrev_b32_e32 v106, 16, v46
	v_and_b32_e32 v107, 0xffff0000, v46
	v_pk_fma_f32 v[32:33], v[76:77], v[106:107], v[32:33]
	v_lshlrev_b32_e32 v106, 16, v47
	v_and_b32_e32 v107, 0xffff0000, v47
	v_pk_fma_f32 v[34:35], v[78:79], v[106:107], v[34:35]
	v_lshlrev_b32_e32 v106, 16, v48
	v_and_b32_e32 v107, 0xffff0000, v48
	v_pk_fma_f32 v[36:37], v[80:81], v[106:107], v[36:37]
	v_lshlrev_b32_e32 v106, 16, v49
	v_and_b32_e32 v107, 0xffff0000, v49
	v_pk_fma_f32 v[38:39], v[82:83], v[106:107], v[38:39]
	v_lshlrev_b32_e32 v106, 16, v50
	v_and_b32_e32 v107, 0xffff0000, v50
	v_pk_fma_f32 v[32:33], v[84:85], v[106:107], v[32:33]
	v_lshlrev_b32_e32 v106, 16, v51
	v_and_b32_e32 v107, 0xffff0000, v51
	v_pk_fma_f32 v[34:35], v[86:87], v[106:107], v[34:35]
	v_lshlrev_b32_e32 v106, 16, v52
	v_and_b32_e32 v107, 0xffff0000, v52
	v_pk_fma_f32 v[36:37], v[88:89], v[106:107], v[36:37]
	v_lshlrev_b32_e32 v106, 16, v53
	v_and_b32_e32 v107, 0xffff0000, v53
	v_pk_fma_f32 v[38:39], v[90:91], v[106:107], v[38:39]
	v_lshlrev_b32_e32 v106, 16, v54
	v_and_b32_e32 v107, 0xffff0000, v54
	v_pk_fma_f32 v[32:33], v[92:93], v[106:107], v[32:33]
	v_lshlrev_b32_e32 v106, 16, v55
	v_and_b32_e32 v107, 0xffff0000, v55
	v_pk_fma_f32 v[34:35], v[94:95], v[106:107], v[34:35]
	v_cvt_pk_bf16_f32 v110, v36, v37
	v_cvt_pk_bf16_f32 v111, v38, v39
	v_cvt_pk_bf16_f32 v112, v32, v33
	v_cvt_pk_bf16_f32 v113, v34, v35
	s_movk_i32 s3, 0xa00
	v_mad_i64_i32 v[108:109], s[6:7], v56, s3, v[126:127]
	global_store_dwordx4 v[108:109], v[110:113], off
	s_nop 1
	s_add_i32 s2, s2, -1
	s_cmp_lg_u32 s2, 0
	s_cbranch_scc1 .Lconv_loop
	s_waitcnt vmcnt(0)
	v_cmp_lt_u32_e32 vcc, 1, v25
	v_cmp_lt_u32_e64 s[6:7], v25, v26
	v_add_u32_e32 v107, 1, v25
	s_nop 1
	s_and_b64 vcc, vcc, s[6:7]
	s_nop 1
	v_cndmask_b32_e32 v8, 0, v8, vcc
	v_cndmask_b32_e32 v9, 0, v9, vcc
	v_cndmask_b32_e32 v10, 0, v10, vcc
	v_cndmask_b32_e32 v11, 0, v11, vcc
	v_cmp_ne_u32_e32 vcc, 0, v25
	v_cmp_lt_u32_e64 s[6:7], v107, v26
	v_add_u32_e32 v106, 2, v25
	s_nop 1
	s_and_b64 vcc, vcc, s[6:7]
	s_nop 1
	v_cndmask_b32_e32 v12, 0, v12, vcc
	v_cndmask_b32_e32 v13, 0, v13, vcc
	v_cndmask_b32_e32 v14, 0, v14, vcc
	v_cndmask_b32_e32 v15, 0, v15, vcc
	v_cmp_lt_u32_e32 vcc, v106, v26
	v_add_u32_e32 v107, 3, v25
	s_nop 1
	v_cndmask_b32_e32 v16, 0, v16, vcc
	v_cndmask_b32_e32 v17, 0, v17, vcc
	v_cndmask_b32_e32 v18, 0, v18, vcc
	v_cndmask_b32_e32 v19, 0, v19, vcc
	v_cmp_lt_u32_e32 vcc, v107, v26
	s_nop 1
	s_nop 0
	v_cndmask_b32_e32 v20, 0, v20, vcc
	v_cndmask_b32_e32 v21, 0, v21, vcc
	v_cndmask_b32_e32 v22, 0, v22, vcc
	v_cndmask_b32_e32 v23, 0, v23, vcc
	v_lshlrev_b32_e32 v106, 16, v8
	v_and_b32_e32 v107, 0xffff0000, v8
	v_pk_fma_f32 v[4:5], v[64:65], v[106:107], v[96:97]
	v_lshlrev_b32_e32 v106, 16, v9
	v_and_b32_e32 v107, 0xffff0000, v9
	v_pk_fma_f32 v[6:7], v[66:67], v[106:107], v[98:99]
	v_lshlrev_b32_e32 v106, 16, v10
	v_and_b32_e32 v107, 0xffff0000, v10
	v_pk_fma_f32 v[0:1], v[68:69], v[106:107], v[100:101]
	v_lshlrev_b32_e32 v106, 16, v11
	v_and_b32_e32 v107, 0xffff0000, v11
	v_pk_fma_f32 v[2:3], v[70:71], v[106:107], v[102:103]
	v_lshlrev_b32_e32 v106, 16, v12
	v_and_b32_e32 v107, 0xffff0000, v12
	v_pk_fma_f32 v[4:5], v[72:73], v[106:107], v[4:5]
	v_lshlrev_b32_e32 v106, 16, v13
	v_and_b32_e32 v107, 0xffff0000, v13
	v_pk_fma_f32 v[6:7], v[74:75], v[106:107], v[6:7]
	v_lshlrev_b32_e32 v106, 16, v14
	v_and_b32_e32 v107, 0xffff0000, v14
	v_pk_fma_f32 v[0:1], v[76:77], v[106:107], v[0:1]
	v_lshlrev_b32_e32 v106, 16, v15
	v_and_b32_e32 v107, 0xffff0000, v15
	v_pk_fma_f32 v[2:3], v[78:79], v[106:107], v[2:3]
	v_lshlrev_b32_e32 v106, 16, v16
	v_and_b32_e32 v107, 0xffff0000, v16
	v_pk_fma_f32 v[4:5], v[80:81], v[106:107], v[4:5]
	v_lshlrev_b32_e32 v106, 16, v17
	v_and_b32_e32 v107, 0xffff0000, v17
	v_pk_fma_f32 v[6:7], v[82:83], v[106:107], v[6:7]
	v_lshlrev_b32_e32 v106, 16, v18
	v_and_b32_e32 v107, 0xffff0000, v18
	v_pk_fma_f32 v[0:1], v[84:85], v[106:107], v[0:1]
	v_lshlrev_b32_e32 v106, 16, v19
	v_and_b32_e32 v107, 0xffff0000, v19
	v_pk_fma_f32 v[2:3], v[86:87], v[106:107], v[2:3]
	v_lshlrev_b32_e32 v106, 16, v20
	v_and_b32_e32 v107, 0xffff0000, v20
	v_pk_fma_f32 v[4:5], v[88:89], v[106:107], v[4:5]
	v_lshlrev_b32_e32 v106, 16, v21
	v_and_b32_e32 v107, 0xffff0000, v21
	v_pk_fma_f32 v[6:7], v[90:91], v[106:107], v[6:7]
	v_lshlrev_b32_e32 v106, 16, v22
	v_and_b32_e32 v107, 0xffff0000, v22
	v_pk_fma_f32 v[0:1], v[92:93], v[106:107], v[0:1]
	v_lshlrev_b32_e32 v106, 16, v23
	v_and_b32_e32 v107, 0xffff0000, v23
	v_pk_fma_f32 v[2:3], v[94:95], v[106:107], v[2:3]
	v_cvt_pk_bf16_f32 v110, v4, v5
	v_cvt_pk_bf16_f32 v111, v6, v7
	v_cvt_pk_bf16_f32 v112, v0, v1
	v_cvt_pk_bf16_f32 v113, v2, v3
	s_movk_i32 s3, 0xa00
	v_mad_i64_i32 v[108:109], s[6:7], v24, s3, v[126:127]
	global_store_dwordx4 v[108:109], v[110:113], off
	s_nop 1
	v_cmp_gt_u32_e32 vcc, 9, v120
	s_and_saveexec_b64 s[100:101], vcc
	s_cbranch_execz .Lconv_tail_done
; __device__ __forceinline__ unsigned pk2(float lo, float hi) { f32x2_pk v = {lo, hi}; bf16x2_pk b = __builtin_convertvector(v, bf16x2_pk); return __builtin_bit_cast(unsigned, b); }
; __device__ __forceinline__ void rg_conv_phase(const bf16_t* XR, bf16_t* XCV, const float* cw, const float* cb, int gtid, int ngt) {
;     for (int it = gtid; it < MT * 160; it += ngt) { const int m = it / 160, c8 = (it % 160) * 8;
;         int t, L; if (m < ML) { t = m & 2047; L = SEQ; } else { t = (m - ML) & 255; L = CTX; }
;         float o[8];
; #pragma unroll
;         for (int e = 0; e < 8; ++e) o[e] = cb[c8 + e];
; #pragma unroll
;         for (int k = 0; k < 4; ++k) { const int tt = t + k - 2; if (tt < 0 || tt >= L) continue;
;             const u32x4 w = *(const u32x4*)(XR + (size_t)(m + k - 2) * DRNN + c8); const float* wk = cw + k * DRNN + c8;
;             o[0] += wk[0] * bflo(w.x); o[1] += wk[1] * bfhi(w.x); o[2] += wk[2] * bflo(w.y); o[3] += wk[3] * bfhi(w.y); o[4] += wk[4] * bflo(w.z); o[5] += wk[5] * bfhi(w.z); o[6] += wk[6] * bflo(w.w); o[7] += wk[7] * bfhi(w.w); }
;         u32x4 r; r.x = pk2(o[0], o[1]); r.y = pk2(o[2], o[3]); r.z = pk2(o[4], o[5]); r.w = pk2(o[6], o[7]);
;         *(u32x4*)(XCV + (size_t)m * DRNN + c8) = r; }
; }
	v_mov_b32_e32 v24, v121
	s_mov_b32 s3, 0x8000
	v_cmp_gt_i32_e32 vcc, s3, v24
	v_mov_b32_e32 v104, 0x7ff
	v_mov_b32_e32 v105, 0x802
	v_cndmask_b32_e32 v104, v216, v104, vcc
	v_and_b32_e32 v25, v104, v24
	v_bfrev_b32_e32 v104, 4.0
	v_cndmask_b32_e32 v26, v104, v105, vcc
	s_movk_i32 s3, 0xa00
	v_cmp_lt_u32_e32 vcc, 1, v25
	v_cmp_lt_u32_e64 s[6:7], v25, v26
	v_add_u32_e32 v106, -2, v24
	s_nop 1
	s_and_b64 vcc, vcc, s[6:7]
	s_nop 1
	v_cndmask_b32_e32 v106, v24, v106, vcc
	v_mad_i64_i32 v[108:109], s[20:21], v106, s3, v[124:125]
	global_load_dwordx4 v[8:11], v[108:109], off
	v_add_u32_e32 v107, 1, v25
	v_cmp_ne_u32_e32 vcc, 0, v25
	v_cmp_lt_u32_e64 s[6:7], v107, v26
	v_add_u32_e32 v106, -1, v24
	s_nop 1
	s_and_b64 vcc, vcc, s[6:7]
	s_nop 1
	v_cndmask_b32_e32 v106, v24, v106, vcc
	v_mad_i64_i32 v[108:109], s[20:21], v106, s3, v[124:125]
	global_load_dwordx4 v[12:15], v[108:109], off
	v_mad_i64_i32 v[108:109], s[20:21], v24, s3, v[124:125]
	global_load_dwordx4 v[16:19], v[108:109], off
	v_add_u32_e32 v107, 3, v25
	v_add_u32_e32 v106, 1, v24
	v_cmp_lt_u32_e32 vcc, v107, v26
	s_nop 1
	v_cndmask_b32_e32 v106, v24, v106, vcc
	v_mad_i64_i32 v[108:109], s[20:21], v106, s3, v[124:125]
	global_load_dwordx4 v[20:23], v[108:109], off
	v_add_u32_e32 v121, 0x333, v121
	s_waitcnt vmcnt(0)
	v_cmp_lt_u32_e32 vcc, 1, v25
	v_cmp_lt_u32_e64 s[6:7], v25, v26
	v_add_u32_e32 v107, 1, v25
	s_nop 1
	s_and_b64 vcc, vcc, s[6:7]
	s_nop 1
	v_cndmask_b32_e32 v8, 0, v8, vcc
	v_cndmask_b32_e32 v9, 0, v9, vcc
	v_cndmask_b32_e32 v10, 0, v10, vcc
	v_cndmask_b32_e32 v11, 0, v11, vcc
	v_cmp_ne_u32_e32 vcc, 0, v25
	v_cmp_lt_u32_e64 s[6:7], v107, v26
	v_add_u32_e32 v106, 2, v25
	s_nop 1
	s_and_b64 vcc, vcc, s[6:7]
	s_nop 1
	v_cndmask_b32_e32 v12, 0, v12, vcc
	v_cndmask_b32_e32 v13, 0, v13, vcc
	v_cndmask_b32_e32 v14, 0, v14, vcc
	v_cndmask_b32_e32 v15, 0, v15, vcc
	v_cmp_lt_u32_e32 vcc, v106, v26
	v_add_u32_e32 v107, 3, v25
	s_nop 1
	v_cndmask_b32_e32 v16, 0, v16, vcc
	v_cndmask_b32_e32 v17, 0, v17, vcc
	v_cndmask_b32_e32 v18, 0, v18, vcc
	v_cndmask_b32_e32 v19, 0, v19, vcc
	v_cmp_lt_u32_e32 vcc, v107, v26
	s_nop 1
	s_nop 0
	v_cndmask_b32_e32 v20, 0, v20, vcc
	v_cndmask_b32_e32 v21, 0, v21, vcc
	v_cndmask_b32_e32 v22, 0, v22, vcc
	v_cndmask_b32_e32 v23, 0, v23, vcc
	v_lshlrev_b32_e32 v106, 16, v8
	v_and_b32_e32 v107, 0xffff0000, v8
	v_pk_fma_f32 v[4:5], v[64:65], v[106:107], v[96:97]
	v_lshlrev_b32_e32 v106, 16, v9
	v_and_b32_e32 v107, 0xffff0000, v9
	v_pk_fma_f32 v[6:7], v[66:67], v[106:107], v[98:99]
	v_lshlrev_b32_e32 v106, 16, v10
	v_and_b32_e32 v107, 0xffff0000, v10
	v_pk_fma_f32 v[0:1], v[68:69], v[106:107], v[100:101]
	v_lshlrev_b32_e32 v106, 16, v11
	v_and_b32_e32 v107, 0xffff0000, v11
	v_pk_fma_f32 v[2:3], v[70:71], v[106:107], v[102:103]
	v_lshlrev_b32_e32 v106, 16, v12
	v_and_b32_e32 v107, 0xffff0000, v12
	v_pk_fma_f32 v[4:5], v[72:73], v[106:107], v[4:5]
	v_lshlrev_b32_e32 v106, 16, v13
	v_and_b32_e32 v107, 0xffff0000, v13
	v_pk_fma_f32 v[6:7], v[74:75], v[106:107], v[6:7]
	v_lshlrev_b32_e32 v106, 16, v14
	v_and_b32_e32 v107, 0xffff0000, v14
	v_pk_fma_f32 v[0:1], v[76:77], v[106:107], v[0:1]
	v_lshlrev_b32_e32 v106, 16, v15
	v_and_b32_e32 v107, 0xffff0000, v15
	v_pk_fma_f32 v[2:3], v[78:79], v[106:107], v[2:3]
	v_lshlrev_b32_e32 v106, 16, v16
	v_and_b32_e32 v107, 0xffff0000, v16
	v_pk_fma_f32 v[4:5], v[80:81], v[106:107], v[4:5]
	v_lshlrev_b32_e32 v106, 16, v17
	v_and_b32_e32 v107, 0xffff0000, v17
	v_pk_fma_f32 v[6:7], v[82:83], v[106:107], v[6:7]
	v_lshlrev_b32_e32 v106, 16, v18
	v_and_b32_e32 v107, 0xffff0000, v18
	v_pk_fma_f32 v[0:1], v[84:85], v[106:107], v[0:1]
	v_lshlrev_b32_e32 v106, 16, v19
	v_and_b32_e32 v107, 0xffff0000, v19
	v_pk_fma_f32 v[2:3], v[86:87], v[106:107], v[2:3]
	v_lshlrev_b32_e32 v106, 16, v20
	v_and_b32_e32 v107, 0xffff0000, v20
	v_pk_fma_f32 v[4:5], v[88:89], v[106:107], v[4:5]
	v_lshlrev_b32_e32 v106, 16, v21
	v_and_b32_e32 v107, 0xffff0000, v21
	v_pk_fma_f32 v[6:7], v[90:91], v[106:107], v[6:7]
	v_lshlrev_b32_e32 v106, 16, v22
	v_and_b32_e32 v107, 0xffff0000, v22
	v_pk_fma_f32 v[0:1], v[92:93], v[106:107], v[0:1]
	v_lshlrev_b32_e32 v106, 16, v23
	v_and_b32_e32 v107, 0xffff0000, v23
	v_pk_fma_f32 v[2:3], v[94:95], v[106:107], v[2:3]
	v_cvt_pk_bf16_f32 v110, v4, v5
	v_cvt_pk_bf16_f32 v111, v6, v7
	v_cvt_pk_bf16_f32 v112, v0, v1
	v_cvt_pk_bf16_f32 v113, v2, v3
	s_movk_i32 s3, 0xa00
	v_mad_i64_i32 v[108:109], s[6:7], v24, s3, v[126:127]
	global_store_dwordx4 v[108:109], v[110:113], off
	s_nop 1
.Lconv_tail_done:
	s_or_b64 exec, exec, s[100:101]
.Lconv_done:
	s_or_b64 exec, exec, s[18:19]
.LBB0_826:
	s_or_b64 exec, exec, s[16:17]
